# adds attention mainloop: 16 exponentials moved from in front of the per-tile barrier to behind the fragment reads that follow it; first grid barrier: the 16 census loads issued together
# baseline (speedup 1.0000x reference)
; __device__ __forceinline__ unsigned xb_ld(unsigned* p)              { return __hip_atomic_load(p, __ATOMIC_RELAXED, __HIP_MEMORY_SCOPE_AGENT); }
; __device__ __forceinline__ void xcd_barrier_complete(unsigned* bar, unsigned x, unsigned& nloc, unsigned& nx) {
;     ...
;     for (;;) {
;         sum = 0u; cnt = 0u; mine = 0u;
; #pragma unroll
;         for (unsigned j = 0; j < 16; ++j) { const unsigned c = xb_ld(&bar[XB_XCNT(j)]); sum += c; cnt += (c > 0u) ? 1u : 0u; mine = (j == x) ? c : mine; }
;         if (sum == G) break;
;         __builtin_amdgcn_s_sleep(1);
;         if ((++sp & 255u) == 0u) { if (xb_ld(&bar[XB_TMO])) break; if (sp > XB_SPIN_CAP) { atomicAdd(&bar[XB_TMO], 1u); break; } }
;     }
.LBB0_116:
	v_readlane_b32 s4, v253, 36
	v_readlane_b32 s5, v253, 37
	global_load_dword v2, v16, s[96:97] sc1
	global_load_dword v0, v16, s[92:93] sc1
	global_load_dword v1, v16, s[14:15] sc1
	s_mov_b64 s[10:11], -1
	s_mov_b64 s[34:35], -1
	global_load_dword v3, v16, s[4:5] sc1
	v_readlane_b32 s4, v253, 38
	v_readlane_b32 s5, v253, 39
	s_nop 4
	global_load_dword v4, v16, s[4:5] sc1
	v_readlane_b32 s4, v253, 40
	v_readlane_b32 s5, v253, 41
	s_nop 4
	global_load_dword v5, v16, s[4:5] sc1
	v_readlane_b32 s4, v253, 42
	v_readlane_b32 s5, v253, 43
	s_nop 4
	global_load_dword v6, v16, s[4:5] sc1
	v_readlane_b32 s4, v253, 44
	v_readlane_b32 s5, v253, 45
	s_nop 4
	global_load_dword v7, v16, s[4:5] sc1
	v_readlane_b32 s4, v253, 46
	v_readlane_b32 s5, v253, 47
	s_nop 4
	global_load_dword v8, v16, s[4:5] sc1
	v_readlane_b32 s4, v253, 48
	v_readlane_b32 s5, v253, 49
	s_nop 4
	global_load_dword v9, v16, s[4:5] sc1
	v_readlane_b32 s4, v253, 50
	v_readlane_b32 s5, v253, 51
	s_nop 4
	global_load_dword v10, v16, s[4:5] sc1
	v_readlane_b32 s4, v253, 52
	v_readlane_b32 s5, v253, 53
	s_nop 4
	global_load_dword v11, v16, s[4:5] sc1
	v_readlane_b32 s4, v253, 54
	v_readlane_b32 s5, v253, 55
	s_nop 4
	global_load_dword v12, v16, s[4:5] sc1
	v_readlane_b32 s4, v253, 56
	v_readlane_b32 s5, v253, 57
	s_nop 4
	global_load_dword v13, v16, s[4:5] sc1
	v_readlane_b32 s4, v253, 58
	v_readlane_b32 s5, v253, 59
	s_nop 4
	global_load_dword v14, v16, s[4:5] sc1
	v_readlane_b32 s4, v253, 60
	v_readlane_b32 s5, v253, 61
	s_nop 4
	global_load_dword v15, v16, s[4:5] sc1
	s_waitcnt vmcnt(0)
	v_add_u32_e32 v17, v0, v2
	v_add_u32_e32 v17, v17, v1
	v_add_u32_e32 v17, v17, v3
	v_add_u32_e32 v17, v17, v4
	v_add_u32_e32 v17, v17, v5
	v_add_u32_e32 v17, v17, v6
	v_add_u32_e32 v17, v17, v7
	v_add_u32_e32 v17, v17, v8
	v_add_u32_e32 v17, v17, v9
	v_add_u32_e32 v17, v17, v10
	v_add_u32_e32 v17, v17, v11
	v_add_u32_e32 v17, v17, v12
	v_add_u32_e32 v17, v17, v13
	v_add_u32_e32 v17, v17, v14
	v_add_u32_e32 v17, v17, v15
	v_cmp_eq_u32_e32 vcc, s6, v17
	s_cbranch_vccnz .LBB0_115
	s_and_b32 s4, s3, 0xff
	s_cmp_eq_u32 s4, 0
	s_mov_b64 s[4:5], -1
	s_sleep 1
	s_cbranch_scc1 .LBB0_120
	s_and_b64 vcc, exec, s[4:5]
	s_cbranch_vccz .LBB0_115

; __device__ __forceinline__ void partialSM(f32x16& p0, f32x16& p1, float& m_reg, float& mn, float& alpha, bool bounded) {
;     ...
;   for (int r = 0; r < 16; ++r) p0[r] = __builtin_amdgcn_exp2f(p0[r]);
; }
; __device__ __forceinline__ void finishSM(f32x16& p0, f32x16& p1, float alpha, float& l_reg, bf16x8& pa0, bf16x8& pa1, bf16x8& pa2, bf16x8& pa3) {
;   for (int r = 0; r < 16; ++r) p1[r] = __builtin_amdgcn_exp2f(p1[r]);
;   float ps = 0; for (int r = 0; r < 16; ++r) ps += p0[r]; for (int r = 0; r < 16; ++r) ps += p1[r];
;   { auto rr = __builtin_amdgcn_permlane32_swap(__float_as_uint(ps), __float_as_uint(ps), false, false);
;     ps = __uint_as_float(rr[0]) + __uint_as_float(rr[1]); }
;   l_reg = l_reg * alpha + ps;
;     ...
;   PK4(p0, 0, pa0); PK4(p0, 8, pa1); PK4(p1, 0, pa2); PK4(p1, 8, pa3);
;     ...
; }
; __device__ __forceinline__ void qkt(f32x16& p0, f32x16& p1, const bf16* Ks, const bf16x8* qr, int r32, int hi) {
;   p0 = f32x16{}; p1 = f32x16{};
;   for (int d0 = 0; d0 < 8; ++d0) { int cb = (d0 * 16 + hi * 8) * 2;
;     bf16x8 b0 = *reinterpret_cast<const bf16x8*>((const char*)Ks + KSWZ(r32, cb));
;     bf16x8 b1 = *reinterpret_cast<const bf16x8*>((const char*)Ks + KSWZ(32 + r32, cb));
;     p0 = __builtin_amdgcn_mfma_f32_32x32x16_bf16(b0, qr[d0], p0, 0, 0, 0);
;     p1 = __builtin_amdgcn_mfma_f32_32x32x16_bf16(b1, qr[d0], p1, 0, 0, 0); }
; }
.LBB0_900:
	s_waitcnt lgkmcnt(0)
	s_barrier
	v_add_u32_e32 v68, s12, v213
	ds_read_b128 v[64:67], v68 offset:49152
	ds_read_b128 v[68:71], v68 offset:57344
	v_add_u32_e32 v226, s12, v215
	ds_read_b128 v[222:225], v226 offset:49152
	ds_read_b128 v[226:229], v226 offset:57344
	v_exp_f32_e32 v220, v96
	v_exp_f32_e32 v230, v97
	v_exp_f32_e32 v231, v98
	v_exp_f32_e32 v232, v99
	v_exp_f32_e32 v233, v100
	v_exp_f32_e32 v234, v101
	v_exp_f32_e32 v235, v102
	v_exp_f32_e32 v236, v103
	v_exp_f32_e32 v237, v104
	v_exp_f32_e32 v238, v105
	v_exp_f32_e32 v239, v106
	v_exp_f32_e32 v240, v107
	v_exp_f32_e32 v241, v108
	v_exp_f32_e32 v242, v109
	v_exp_f32_e32 v243, v110
	v_exp_f32_e32 v244, v111
	v_exp_f32_e32 v245, v86
	s_waitcnt lgkmcnt(3)
	v_mfma_f32_32x32x16_bf16 v[96:111], v[64:67], v[136:139], 0
	v_exp_f32_e32 v246, v87
	v_exp_f32_e32 v247, v88
	v_exp_f32_e32 v248, v89
	v_exp_f32_e32 v249, v90
	v_exp_f32_e32 v250, v91
	v_exp_f32_e32 v251, v92
	v_exp_f32_e32 v252, v93
	s_waitcnt lgkmcnt(2)
	v_mfma_f32_32x32x16_bf16 v[64:79], v[68:71], v[136:139], 0
	v_exp_f32_e32 v194, v94
	v_exp_f32_e32 v95, v95
	s_waitcnt lgkmcnt(1)
	v_mfma_f32_32x32x16_bf16 v[96:111], v[222:225], v[140:143], v[96:111]
	s_waitcnt lgkmcnt(0)
	v_mfma_f32_32x32x16_bf16 v[64:79], v[226:229], v[140:143], v[64:79]
	v_add_u32_e32 v226, s12, v214
	ds_read_b128 v[222:225], v226 offset:49152
	ds_read_b128 v[226:229], v226 offset:57344
	s_waitcnt lgkmcnt(1)
	v_mfma_f32_32x32x16_bf16 v[96:111], v[222:225], v[128:131], v[96:111]
	s_waitcnt lgkmcnt(0)
	v_mfma_f32_32x32x16_bf16 v[64:79], v[226:229], v[128:131], v[64:79]
	v_add_u32_e32 v226, s12, v211
	ds_read_b128 v[222:225], v226 offset:49152
	ds_read_b128 v[226:229], v226 offset:57344
	s_waitcnt lgkmcnt(1)
	v_mfma_f32_32x32x16_bf16 v[96:111], v[222:225], v[132:135], v[96:111]
	s_waitcnt lgkmcnt(0)
	v_mfma_f32_32x32x16_bf16 v[64:79], v[226:229], v[132:135], v[64:79]
	v_add_u32_e32 v226, s12, v209
	ds_read_b128 v[222:225], v226 offset:49152
	ds_read_b128 v[226:229], v226 offset:57344
	s_waitcnt lgkmcnt(1)
	v_mfma_f32_32x32x16_bf16 v[96:111], v[222:225], v[124:127], v[96:111]
	s_waitcnt lgkmcnt(0)
	v_mfma_f32_32x32x16_bf16 v[64:79], v[226:229], v[124:127], v[64:79]
	v_add_u32_e32 v226, s12, v206
	ds_read_b128 v[222:225], v226 offset:49152
	ds_read_b128 v[226:229], v226 offset:57344
	s_waitcnt lgkmcnt(1)
	v_mfma_f32_32x32x16_bf16 v[96:111], v[222:225], v[116:119], v[96:111]
	s_waitcnt lgkmcnt(0)
	v_mfma_f32_32x32x16_bf16 v[64:79], v[226:229], v[116:119], v[64:79]
	v_add_u32_e32 v226, s12, v207
	ds_read_b128 v[222:225], v226 offset:49152
	ds_read_b128 v[226:229], v226 offset:57344
	s_waitcnt lgkmcnt(1)
	v_mfma_f32_32x32x16_bf16 v[96:111], v[222:225], v[120:123], v[96:111]
	s_waitcnt lgkmcnt(0)
	v_mfma_f32_32x32x16_bf16 v[64:79], v[226:229], v[120:123], v[64:79]
	v_add_u32_e32 v226, s12, v212
	ds_read_b128 v[222:225], v226 offset:49152
	ds_read_b128 v[226:229], v226 offset:57344
	s_waitcnt lgkmcnt(1)
	v_mfma_f32_32x32x16_bf16 v[96:111], v[222:225], v[112:115], v[96:111]
	v_exp_f32_e32 v224, v80
	v_add_f32_e32 v80, 0, v220
	v_add_f32_e32 v80, v230, v80
	v_add_f32_e32 v80, v231, v80
	v_add_f32_e32 v80, v232, v80
	v_add_f32_e32 v80, v233, v80
	v_add_f32_e32 v80, v234, v80
	v_add_f32_e32 v80, v235, v80
	v_add_f32_e32 v80, v236, v80
	v_add_f32_e32 v80, v237, v80
	v_add_f32_e32 v80, v238, v80
	v_add_f32_e32 v80, v239, v80
	v_add_f32_e32 v80, v240, v80
	v_add_f32_e32 v80, v241, v80
	v_exp_f32_e32 v225, v81
	v_add_f32_e32 v80, v242, v80
	s_waitcnt lgkmcnt(0)
	v_mfma_f32_32x32x16_bf16 v[64:79], v[226:229], v[112:115], v[64:79]
	v_exp_f32_e32 v226, v82
	v_add_f32_e32 v80, v243, v80
	v_exp_f32_e32 v227, v83
	v_add_f32_e32 v80, v244, v80
	v_exp_f32_e32 v228, v84
	v_add_f32_e32 v80, v224, v80
	v_exp_f32_e32 v229, v85
	v_add_f32_e32 v80, v225, v80
	v_add_f32_e32 v80, v226, v80
	v_add_f32_e32 v80, v227, v80
	v_add_f32_e32 v80, v228, v80
	v_add_f32_e32 v80, v229, v80
	v_add_f32_e32 v80, v245, v80
	v_add_f32_e32 v80, v246, v80
	v_add_f32_e32 v80, v247, v80
	v_add_f32_e32 v80, v248, v80
	v_add_f32_e32 v80, v249, v80
	v_add_f32_e32 v80, v250, v80
	v_add_f32_e32 v80, v251, v80
	v_add_f32_e32 v80, v252, v80
	v_add_f32_e32 v80, v194, v80
	v_add_f32_e32 v222, v95, v80
	v_mov_b32_e32 v223, v222
	v_cvt_pk_bf16_f32 v80, v220, v230
	v_cvt_pk_bf16_f32 v81, v231, v232
	v_cvt_pk_bf16_f32 v82, v233, v234
	v_cvt_pk_bf16_f32 v83, v235, v236
	v_cvt_pk_bf16_f32 v84, v237, v238
	v_cvt_pk_bf16_f32 v85, v239, v240
	v_cvt_pk_bf16_f32 v86, v241, v242
	v_cvt_pk_bf16_f32 v87, v243, v244
	v_cvt_pk_bf16_f32 v88, v224, v225
	v_cvt_pk_bf16_f32 v89, v226, v227
	v_cvt_pk_bf16_f32 v90, v228, v229
	v_cvt_pk_bf16_f32 v91, v245, v246
	v_cvt_pk_bf16_f32 v92, v247, v248
	v_cvt_pk_bf16_f32 v93, v249, v250
	v_cvt_pk_bf16_f32 v94, v251, v252
	v_cvt_pk_bf16_f32 v95, v194, v95
	s_nop 1
	v_permlane32_swap_b32_e32 v222, v223
	v_permlane32_swap_b32_e32 v80, v82
	v_permlane32_swap_b32_e32 v81, v83
	v_permlane32_swap_b32_e32 v84, v86
	v_permlane32_swap_b32_e32 v85, v87
	v_permlane32_swap_b32_e32 v88, v90
	v_permlane32_swap_b32_e32 v89, v91
	v_permlane32_swap_b32_e32 v92, v94
	v_permlane32_swap_b32_e32 v93, v95
	s_cmpk_gt_u32 s3, 0x80
	s_cselect_b64 s[34:35], -1, 0
	s_and_b64 vcc, exec, s[34:35]
	s_cbranch_vccnz .LBB0_902
	v_add_co_u32_e32 v144, vcc, 0xffffe000, v182
	s_nop 1
	v_addc_co_u32_e32 v145, vcc, -1, v183, vcc
	v_add_co_u32_e32 v148, vcc, 0xfeefe000, v182
	s_nop 1
	v_addc_co_u32_e32 v149, vcc, -1, v183, vcc
	v_add_co_u32_e32 v156, vcc, 0xfef00000, v182
	global_load_dwordx4 v[144:147], v[144:145], off
	s_nop 0
	global_load_dwordx4 v[148:151], v[148:149], off
	v_addc_co_u32_e32 v157, vcc, -1, v183, vcc
	global_load_dwordx4 v[152:155], v[182:183], off
	s_nop 0
	global_load_dwordx4 v[156:159], v[156:157], off
